# P8 loop: per-segment s_setprio flips removed, one static s_setprio 1 for waves 4-7 (younger half) before the tile loop
# speedup vs baseline: 1.0169x; 1.0068x over previous
.LBB0_1093:
	s_lshl_b32 s4, s4, 5
	s_and_b32 s10, s4, 0x60
	s_lshl_b32 s6, s55, 13
	s_lshl_b32 s7, s10, 7
	s_add_u32 s22, s18, 0xa5b8000
	s_addc_u32 s23, s19, 0
	s_add_u32 s24, s18, 0x15b38000
	s_addc_u32 s25, s19, 0
	s_add_u32 s26, s18, 0x17138000
	s_addc_u32 s27, s19, 0
	s_add_u32 s28, s18, 0x18738000
	s_addc_u32 s29, s19, 0
	s_ashr_i32 s63, s33, 31
	s_add_u32 s30, s12, 0xb000
	s_addc_u32 s31, s13, 0
	s_add_u32 s34, s12, 0x16000
	s_mov_b64 s[36:37], 0x80
	s_addc_u32 s35, s13, 0
	s_add_i32 m0, s21, 0x18000
	v_lshl_add_u64 v[8:9], v[8:9], 0, s[36:37]
	s_waitcnt vmcnt(4)
	s_barrier
	global_load_lds_dwordx4 v[8:9], off
	v_lshl_add_u64 v[6:7], v[6:7], 0, s[36:37]
	s_add_i32 m0, s21, 0x1a000
	s_add_i32 s64, s21, 0x8000
	s_add_i32 s65, s21, 0xa000
	global_load_lds_dwordx4 v[6:7], off
	v_lshl_add_u64 v[4:5], v[4:5], 0, s[36:37]
	s_mov_b32 m0, s64
	s_add_u32 s4, s50, 0x80080
	global_load_lds_dwordx4 v[4:5], off
	v_lshl_add_u64 v[2:3], v[2:3], 0, s[36:37]
	s_mov_b32 m0, s65
	s_addc_u32 s5, s51, 0
	global_load_lds_dwordx4 v[2:3], off
	s_add_i32 m0, s21, 0x1c000
	v_lshl_add_u64 v[2:3], s[4:5], 0, v[162:163]
	global_load_lds_dwordx4 v[2:3], off
	v_lshl_add_u64 v[2:3], s[4:5], 0, v[164:165]
	s_add_i32 m0, s21, 0x1e000
	v_lshlrev_b32_e32 v4, 6, v10
	global_load_lds_dwordx4 v[2:3], off
	v_bfe_u32 v2, v10, 4, 2
	v_lshlrev_b32_e32 v3, 4, v2
	s_movk_i32 s4, 0x3c0
	v_lshlrev_b32_e32 v5, 2, v10
	v_and_or_b32 v4, v4, s4, v3
	v_and_b32_e32 v5, 32, v5
	v_lshl_or_b32 v239, v2, 2, s10
	v_lshlrev_b32_e32 v2, 9, v10
	v_bitop3_b32 v236, s7, v4, v5 bitop3:0xf6
	v_and_b32_e32 v2, 0x70000, v2
	v_lshlrev_b32_e32 v4, 12, v13
	v_or3_b32 v2, v11, v2, v4
	v_and_b32_e32 v1, 15, v10
	v_add_u32_e32 v166, v2, v12
	v_lshlrev_b32_e32 v2, 5, v14
	v_lshl_or_b32 v3, v1, 6, v3
	s_waitcnt vmcnt(6)
	v_and_b32_e32 v2, 0xf0000, v2
	v_lshl_or_b32 v6, s55, 6, v1
	v_bitop3_b32 v3, v3, s6, v5 bitop3:0xde
	v_or3_b32 v2, v11, v2, v4
	s_add_i32 s68, 0, 0x10000
	s_add_i32 s69, 0, 0x14000
	v_cmp_gt_u32_e64 s[4:5], 2, v1
	v_cmp_lt_u32_e64 s[6:7], 13, v1
	v_add_u32_e32 v237, -14, v1
	v_cmp_lt_u32_e64 s[8:9], 1, v1
	v_add_u32_e32 v238, 0xffffc000, v6
	s_ashr_i32 s66, s3, 31
	v_mov_b32_e32 v167, v163
	v_add_u32_e32 v170, v2, v12
	v_mov_b32_e32 v171, v163
	v_mov_b64_e32 v[172:173], 0xbb0
	v_mov_b64_e32 v[174:175], 0xbaf
	s_movk_i32 s67, 0x16c
	s_mov_b32 s87, 28
	v_and_b32_e32 v245, 31, v0
	v_lshlrev_b32_e32 v245, 4, v245
	v_bfe_u32 v250, v0, 5, 1
	v_mul_u32_u24_e32 v250, 0x5800, v250
	v_add_u32_e32 v245, v245, v250
	v_lshlrev_b32_e32 v250, 2, v239
	s_mov_b32 s86, 0x20000
	s_cmpk_gt_u32 s56, 0xfff
	s_cbranch_scc0 .Lp8_prio_done
	s_setprio 1
.Lp8_prio_done:
	v_add_u32_e32 v240, s68, v236
	v_add_u32_e32 v241, 0, v3
	v_add_u32_e32 v242, s69, v236
	s_movk_i32 s70, 0x5000
	s_mov_b32 s71, 0xb000
	s_movk_i32 s72, 0x2c00
	s_barrier
	s_branch .LBB0_1095

.Lp8_nostage:
	v_add_u32_e32 v168, 0x18000, v236
	v_add_u32_e32 v169, 0x1c000, v236
	ds_read_b128 v[130:133], v240
	ds_read_b128 v[134:137], v240 offset:1024
	ds_read_b128 v[138:141], v240 offset:2048
	ds_read_b128 v[142:145], v240 offset:3072
	ds_read_b128 v[146:149], v241
	ds_read_b128 v[150:153], v241 offset:1024
	ds_read_b128 v[154:157], v241 offset:2048
	ds_read_b128 v[158:161], v241 offset:3072
	ds_read_b128 v[176:179], v241 offset:4096
	ds_read_b128 v[180:183], v241 offset:5120
	ds_read_b128 v[184:187], v241 offset:6144
	ds_read_b128 v[188:191], v241 offset:7168
	s_add_u32 s50, s48, 0xfff80080
	s_addc_u32 s51, s49, -1
	s_cmp_eq_u32 s80, s87
	s_cselect_b32 s53, s41, s51
	s_cselect_b32 s52, s47, s50
	s_cselect_b32 s51, s39, s75
	s_cselect_b32 s50, s73, s74
	s_add_i32 m0, s21, 0xc000
	s_nop 0
	global_load_lds_dwordx4 v166, s[48:49]
	s_add_i32 m0, s21, 0xe000
	s_nop 0
	global_load_lds_dwordx4 v170, s[48:49]
	s_waitcnt vmcnt(10)
	s_barrier
	s_waitcnt lgkmcnt(0)
	v_mfma_f32_16x16x32_bf16 v[126:129], v[130:133], v[146:149], 0
	ds_read_b128 v[192:195], v242
	v_mfma_f32_16x16x32_bf16 v[122:125], v[138:141], v[146:149], 0
	v_mfma_f32_16x16x32_bf16 v[118:121], v[130:133], v[154:157], 0
	v_mfma_f32_16x16x32_bf16 v[114:117], v[138:141], v[154:157], 0
	v_mfma_f32_16x16x32_bf16 v[106:109], v[130:133], v[176:179], 0
	ds_read_b128 v[196:199], v242 offset:1024
	v_mfma_f32_16x16x32_bf16 v[98:101], v[138:141], v[176:179], 0
	v_mfma_f32_16x16x32_bf16 v[90:93], v[130:133], v[184:187], 0
	v_mfma_f32_16x16x32_bf16 v[82:85], v[138:141], v[184:187], 0
	v_mfma_f32_16x16x32_bf16 v[126:129], v[134:137], v[150:153], v[126:129]
	ds_read_b128 v[200:203], v242 offset:2048
	v_mfma_f32_16x16x32_bf16 v[122:125], v[142:145], v[150:153], v[122:125]
	v_mfma_f32_16x16x32_bf16 v[118:121], v[134:137], v[158:161], v[118:121]
	v_mfma_f32_16x16x32_bf16 v[114:117], v[142:145], v[158:161], v[114:117]
	v_mfma_f32_16x16x32_bf16 v[106:109], v[134:137], v[180:183], v[106:109]
	ds_read_b128 v[204:207], v242 offset:3072
	v_mfma_f32_16x16x32_bf16 v[98:101], v[142:145], v[180:183], v[98:101]
	v_mfma_f32_16x16x32_bf16 v[90:93], v[134:137], v[188:191], v[90:93]
	v_mfma_f32_16x16x32_bf16 v[82:85], v[142:145], v[188:191], v[82:85]
	s_barrier
	s_add_i32 s81, s68, s56
	s_add_u32 s96, s50, 0x80
	s_addc_u32 s97, s51, 0
	s_mov_b32 m0, s81
	s_nop 0
	global_load_lds_dwordx4 v162, s[50:51]
	s_add_i32 m0, s81, 0x2000
	s_nop 0
	global_load_lds_dwordx4 v164, s[50:51]
	s_waitcnt vmcnt(10)
	s_barrier
	s_waitcnt lgkmcnt(0)
	v_mfma_f32_16x16x32_bf16 v[110:113], v[192:195], v[146:149], 0
	ds_read_b128 v[208:211], v241 offset:16384
	v_mfma_f32_16x16x32_bf16 v[102:105], v[200:203], v[146:149], 0
	v_mfma_f32_16x16x32_bf16 v[94:97], v[192:195], v[154:157], 0
	ds_read_b128 v[212:215], v241 offset:17408
	v_mfma_f32_16x16x32_bf16 v[86:89], v[200:203], v[154:157], 0
	v_mfma_f32_16x16x32_bf16 v[78:81], v[192:195], v[176:179], 0
	ds_read_b128 v[216:219], v241 offset:18432
	v_mfma_f32_16x16x32_bf16 v[74:77], v[200:203], v[176:179], 0
	v_mfma_f32_16x16x32_bf16 v[70:73], v[192:195], v[184:187], 0
	ds_read_b128 v[220:223], v241 offset:19456
	v_mfma_f32_16x16x32_bf16 v[66:69], v[200:203], v[184:187], 0
	v_mfma_f32_16x16x32_bf16 v[110:113], v[196:199], v[150:153], v[110:113]
	ds_read_b128 v[224:227], v241 offset:20480
	v_mfma_f32_16x16x32_bf16 v[102:105], v[204:207], v[150:153], v[102:105]
	v_mfma_f32_16x16x32_bf16 v[94:97], v[196:199], v[158:161], v[94:97]
	ds_read_b128 v[228:231], v241 offset:21504
	v_mfma_f32_16x16x32_bf16 v[86:89], v[204:207], v[158:161], v[86:89]
	v_mfma_f32_16x16x32_bf16 v[78:81], v[196:199], v[180:183], v[78:81]
	ds_read_b128 v[232:235], v241 offset:22528
	v_mfma_f32_16x16x32_bf16 v[74:77], v[204:207], v[180:183], v[74:77]
	v_mfma_f32_16x16x32_bf16 v[70:73], v[196:199], v[188:191], v[70:73]
	ds_read_b128 v[246:249], v241 offset:23552
	v_mfma_f32_16x16x32_bf16 v[66:69], v[204:207], v[188:191], v[66:69]
	s_barrier
	s_mov_b32 m0, s21
	s_add_u32 s94, s52, 0x80
	s_addc_u32 s95, s53, 0
	global_load_lds_dwordx4 v162, s[52:53]
	s_mov_b32 m0, s59
	s_nop 0
	global_load_lds_dwordx4 v164, s[52:53]
	s_waitcnt vmcnt(8)
	s_barrier
	s_waitcnt lgkmcnt(0)
	v_mfma_f32_16x16x32_bf16 v[62:65], v[130:133], v[208:211], 0
	ds_read_b128 v[146:149], v241 offset:32768
	v_mfma_f32_16x16x32_bf16 v[58:61], v[138:141], v[208:211], 0
	v_mfma_f32_16x16x32_bf16 v[54:57], v[130:133], v[216:219], 0
	ds_read_b128 v[150:153], v241 offset:33792
	v_mfma_f32_16x16x32_bf16 v[50:53], v[138:141], v[216:219], 0
	v_mfma_f32_16x16x32_bf16 v[42:45], v[130:133], v[224:227], 0
	ds_read_b128 v[154:157], v241 offset:34816
	v_mfma_f32_16x16x32_bf16 v[34:37], v[138:141], v[224:227], 0
	v_mfma_f32_16x16x32_bf16 v[26:29], v[130:133], v[232:235], 0
	ds_read_b128 v[158:161], v241 offset:35840
	v_mfma_f32_16x16x32_bf16 v[18:21], v[138:141], v[232:235], 0
	v_mfma_f32_16x16x32_bf16 v[62:65], v[134:137], v[212:215], v[62:65]
	ds_read_b128 v[176:179], v241 offset:36864
	v_mfma_f32_16x16x32_bf16 v[58:61], v[142:145], v[212:215], v[58:61]
	v_mfma_f32_16x16x32_bf16 v[54:57], v[134:137], v[220:223], v[54:57]
	ds_read_b128 v[180:183], v241 offset:37888
	v_mfma_f32_16x16x32_bf16 v[50:53], v[142:145], v[220:223], v[50:53]
	v_mfma_f32_16x16x32_bf16 v[42:45], v[134:137], v[228:231], v[42:45]
	ds_read_b128 v[184:187], v241 offset:38912
	v_mfma_f32_16x16x32_bf16 v[34:37], v[142:145], v[228:231], v[34:37]
	v_mfma_f32_16x16x32_bf16 v[26:29], v[134:137], v[246:249], v[26:29]
	ds_read_b128 v[188:191], v241 offset:39936
	v_mfma_f32_16x16x32_bf16 v[18:21], v[142:145], v[246:249], v[18:21]
	s_barrier
	s_add_u32 s82, s50, 0x80000
	s_addc_u32 s83, s51, 0
	s_add_i32 s81, s69, s56
	s_mov_b32 m0, s81
	s_nop 0
	global_load_lds_dwordx4 v162, s[82:83]
	s_add_i32 m0, s81, 0x2000
	s_nop 0
	global_load_lds_dwordx4 v164, s[82:83]
	s_waitcnt vmcnt(10)
	s_barrier
	s_waitcnt lgkmcnt(0)
	v_mfma_f32_16x16x32_bf16 v[46:49], v[192:195], v[208:211], 0
	ds_read_b128 v[130:133], v168
	v_mfma_f32_16x16x32_bf16 v[38:41], v[200:203], v[208:211], 0
	v_mfma_f32_16x16x32_bf16 v[30:33], v[192:195], v[216:219], 0
	v_mfma_f32_16x16x32_bf16 v[22:25], v[200:203], v[216:219], 0
	v_mfma_f32_16x16x32_bf16 v[14:17], v[192:195], v[224:227], 0
	ds_read_b128 v[134:137], v168 offset:1024
	v_mfma_f32_16x16x32_bf16 v[10:13], v[200:203], v[224:227], 0
	v_mfma_f32_16x16x32_bf16 v[6:9], v[192:195], v[232:235], 0
	v_mfma_f32_16x16x32_bf16 v[2:5], v[200:203], v[232:235], 0
	v_mfma_f32_16x16x32_bf16 v[46:49], v[196:199], v[212:215], v[46:49]
	ds_read_b128 v[138:141], v168 offset:2048
	v_mfma_f32_16x16x32_bf16 v[38:41], v[204:207], v[212:215], v[38:41]
	v_mfma_f32_16x16x32_bf16 v[30:33], v[196:199], v[220:223], v[30:33]
	v_mfma_f32_16x16x32_bf16 v[22:25], v[204:207], v[220:223], v[22:25]
	v_mfma_f32_16x16x32_bf16 v[14:17], v[196:199], v[228:231], v[14:17]
	ds_read_b128 v[142:145], v168 offset:3072
	v_mfma_f32_16x16x32_bf16 v[10:13], v[204:207], v[228:231], v[10:13]
	v_mfma_f32_16x16x32_bf16 v[6:9], v[196:199], v[246:249], v[6:9]
	v_mfma_f32_16x16x32_bf16 v[2:5], v[204:207], v[246:249], v[2:5]
	s_barrier
	s_add_i32 s81, 0, 0x18000
	s_add_u32 s52, s52, 0x80000
	s_addc_u32 s53, s53, 0
	s_mov_b32 m0, s60
	s_nop 0
	global_load_lds_dwordx4 v162, s[52:53]
	s_mov_b32 m0, s61
	s_nop 0
	global_load_lds_dwordx4 v164, s[52:53]
	s_waitcnt vmcnt(10)
	s_barrier
	s_waitcnt lgkmcnt(0)
	v_mfma_f32_16x16x32_bf16 v[126:129], v[130:133], v[146:149], v[126:129]
	ds_read_b128 v[192:195], v169
	v_mfma_f32_16x16x32_bf16 v[122:125], v[138:141], v[146:149], v[122:125]
	v_mfma_f32_16x16x32_bf16 v[118:121], v[130:133], v[154:157], v[118:121]
	v_mfma_f32_16x16x32_bf16 v[114:117], v[138:141], v[154:157], v[114:117]
	v_mfma_f32_16x16x32_bf16 v[106:109], v[130:133], v[176:179], v[106:109]
	ds_read_b128 v[196:199], v169 offset:1024
	v_mfma_f32_16x16x32_bf16 v[98:101], v[138:141], v[176:179], v[98:101]
	v_mfma_f32_16x16x32_bf16 v[90:93], v[130:133], v[184:187], v[90:93]
	v_mfma_f32_16x16x32_bf16 v[82:85], v[138:141], v[184:187], v[82:85]
	v_mfma_f32_16x16x32_bf16 v[126:129], v[134:137], v[150:153], v[126:129]
	ds_read_b128 v[200:203], v169 offset:2048
	v_mfma_f32_16x16x32_bf16 v[122:125], v[142:145], v[150:153], v[122:125]
	v_mfma_f32_16x16x32_bf16 v[118:121], v[134:137], v[158:161], v[118:121]
	v_mfma_f32_16x16x32_bf16 v[114:117], v[142:145], v[158:161], v[114:117]
	v_mfma_f32_16x16x32_bf16 v[106:109], v[134:137], v[180:183], v[106:109]
	ds_read_b128 v[204:207], v169 offset:3072
	v_mfma_f32_16x16x32_bf16 v[98:101], v[142:145], v[180:183], v[98:101]
	v_mfma_f32_16x16x32_bf16 v[90:93], v[134:137], v[188:191], v[90:93]
	v_mfma_f32_16x16x32_bf16 v[82:85], v[142:145], v[188:191], v[82:85]
	s_barrier
	s_add_i32 s52, 0, 0x1c000
	s_add_i32 s53, s81, s56
	s_mov_b32 m0, s53
	s_nop 0
	global_load_lds_dwordx4 v162, s[96:97]
	s_add_i32 m0, s53, 0x2000
	s_nop 0
	global_load_lds_dwordx4 v164, s[96:97]
	s_waitcnt vmcnt(10)
	s_barrier
	s_waitcnt lgkmcnt(0)
	v_mfma_f32_16x16x32_bf16 v[110:113], v[192:195], v[146:149], v[110:113]
	ds_read_b128 v[208:211], v241 offset:49152
	v_mfma_f32_16x16x32_bf16 v[102:105], v[200:203], v[146:149], v[102:105]
	v_mfma_f32_16x16x32_bf16 v[94:97], v[192:195], v[154:157], v[94:97]
	ds_read_b128 v[212:215], v241 offset:50176
	v_mfma_f32_16x16x32_bf16 v[86:89], v[200:203], v[154:157], v[86:89]
	v_mfma_f32_16x16x32_bf16 v[78:81], v[192:195], v[176:179], v[78:81]
	ds_read_b128 v[216:219], v241 offset:51200
	v_mfma_f32_16x16x32_bf16 v[74:77], v[200:203], v[176:179], v[74:77]
	v_mfma_f32_16x16x32_bf16 v[70:73], v[192:195], v[184:187], v[70:73]
	ds_read_b128 v[220:223], v241 offset:52224
	v_mfma_f32_16x16x32_bf16 v[66:69], v[200:203], v[184:187], v[66:69]
	v_mfma_f32_16x16x32_bf16 v[110:113], v[196:199], v[150:153], v[110:113]
	ds_read_b128 v[224:227], v241 offset:53248
	v_mfma_f32_16x16x32_bf16 v[102:105], v[204:207], v[150:153], v[102:105]
	v_mfma_f32_16x16x32_bf16 v[94:97], v[196:199], v[158:161], v[94:97]
	ds_read_b128 v[228:231], v241 offset:54272
	v_mfma_f32_16x16x32_bf16 v[86:89], v[204:207], v[158:161], v[86:89]
	v_mfma_f32_16x16x32_bf16 v[78:81], v[196:199], v[180:183], v[78:81]
	ds_read_b128 v[232:235], v241 offset:55296
	v_mfma_f32_16x16x32_bf16 v[74:77], v[204:207], v[180:183], v[74:77]
	v_mfma_f32_16x16x32_bf16 v[70:73], v[196:199], v[188:191], v[70:73]
	ds_read_b128 v[246:249], v241 offset:56320
	v_mfma_f32_16x16x32_bf16 v[66:69], v[204:207], v[188:191], v[66:69]
	s_barrier
	s_mov_b32 m0, s64
	s_nop 0
	global_load_lds_dwordx4 v162, s[94:95]
	s_mov_b32 m0, s65
	s_nop 0
	global_load_lds_dwordx4 v164, s[94:95]
	s_waitcnt vmcnt(8)
	s_barrier
	s_waitcnt lgkmcnt(0)
	v_mfma_f32_16x16x32_bf16 v[62:65], v[130:133], v[208:211], v[62:65]
	ds_read_b128 v[146:149], v241
	v_mfma_f32_16x16x32_bf16 v[58:61], v[138:141], v[208:211], v[58:61]
	v_mfma_f32_16x16x32_bf16 v[54:57], v[130:133], v[216:219], v[54:57]
	ds_read_b128 v[150:153], v241 offset:1024
	v_mfma_f32_16x16x32_bf16 v[50:53], v[138:141], v[216:219], v[50:53]
	v_mfma_f32_16x16x32_bf16 v[42:45], v[130:133], v[224:227], v[42:45]
	ds_read_b128 v[154:157], v241 offset:2048
	v_mfma_f32_16x16x32_bf16 v[34:37], v[138:141], v[224:227], v[34:37]
	v_mfma_f32_16x16x32_bf16 v[26:29], v[130:133], v[232:235], v[26:29]
	ds_read_b128 v[158:161], v241 offset:3072
	v_mfma_f32_16x16x32_bf16 v[18:21], v[138:141], v[232:235], v[18:21]
	v_mfma_f32_16x16x32_bf16 v[62:65], v[134:137], v[212:215], v[62:65]
	ds_read_b128 v[176:179], v241 offset:4096
	v_mfma_f32_16x16x32_bf16 v[58:61], v[142:145], v[212:215], v[58:61]
	v_mfma_f32_16x16x32_bf16 v[54:57], v[134:137], v[220:223], v[54:57]
	ds_read_b128 v[180:183], v241 offset:5120
	v_mfma_f32_16x16x32_bf16 v[50:53], v[142:145], v[220:223], v[50:53]
	v_mfma_f32_16x16x32_bf16 v[42:45], v[134:137], v[228:231], v[42:45]
	ds_read_b128 v[184:187], v241 offset:6144
	v_mfma_f32_16x16x32_bf16 v[34:37], v[142:145], v[228:231], v[34:37]
	v_mfma_f32_16x16x32_bf16 v[26:29], v[134:137], v[246:249], v[26:29]
	ds_read_b128 v[188:191], v241 offset:7168
	v_mfma_f32_16x16x32_bf16 v[18:21], v[142:145], v[246:249], v[18:21]
	s_barrier
	s_add_u32 s50, s50, 0x80080
	s_addc_u32 s51, s51, 0
	s_add_i32 s52, s52, s56
	s_mov_b32 m0, s52
	s_nop 0
	global_load_lds_dwordx4 v162, s[50:51]
	s_add_i32 m0, s52, 0x2000
	s_nop 0
	global_load_lds_dwordx4 v164, s[50:51]
	s_waitcnt vmcnt(10)
	s_barrier
	s_waitcnt lgkmcnt(0)
	v_mfma_f32_16x16x32_bf16 v[46:49], v[192:195], v[208:211], v[46:49]
	ds_read_b128 v[130:133], v240
	v_mfma_f32_16x16x32_bf16 v[38:41], v[200:203], v[208:211], v[38:41]
	v_mfma_f32_16x16x32_bf16 v[30:33], v[192:195], v[216:219], v[30:33]
	v_mfma_f32_16x16x32_bf16 v[22:25], v[200:203], v[216:219], v[22:25]
	v_mfma_f32_16x16x32_bf16 v[14:17], v[192:195], v[224:227], v[14:17]
	ds_read_b128 v[134:137], v240 offset:1024
	v_mfma_f32_16x16x32_bf16 v[10:13], v[200:203], v[224:227], v[10:13]
	v_mfma_f32_16x16x32_bf16 v[6:9], v[192:195], v[232:235], v[6:9]
	v_mfma_f32_16x16x32_bf16 v[2:5], v[200:203], v[232:235], v[2:5]
	v_mfma_f32_16x16x32_bf16 v[46:49], v[196:199], v[212:215], v[46:49]
	ds_read_b128 v[138:141], v240 offset:2048
	v_mfma_f32_16x16x32_bf16 v[38:41], v[204:207], v[212:215], v[38:41]
	v_mfma_f32_16x16x32_bf16 v[30:33], v[196:199], v[220:223], v[30:33]
	v_mfma_f32_16x16x32_bf16 v[22:25], v[204:207], v[220:223], v[22:25]
	v_mfma_f32_16x16x32_bf16 v[14:17], v[196:199], v[228:231], v[14:17]
	ds_read_b128 v[142:145], v240 offset:3072
	v_mfma_f32_16x16x32_bf16 v[10:13], v[204:207], v[228:231], v[10:13]
	v_mfma_f32_16x16x32_bf16 v[6:9], v[196:199], v[246:249], v[6:9]
	v_mfma_f32_16x16x32_bf16 v[2:5], v[204:207], v[246:249], v[2:5]
	s_add_i32 s80, s80, 2
	s_add_u32 s48, s48, 0x100
	s_addc_u32 s49, s49, 0
	s_add_u32 s74, s74, 0x100
	s_addc_u32 s75, s75, 0
	s_cmp_gt_u32 s80, s87
	s_barrier
	s_cbranch_scc0 .LBB0_1098
	s_branch .Lp8_loop_exit
.LBB0_1098:
	s_add_u32 s50, s48, 0xfff80080
	s_addc_u32 s51, s49, -1
	s_cmp_eq_u32 s80, s87
	s_cselect_b32 s53, s41, s51
	s_cselect_b32 s52, s47, s50
	s_cselect_b32 s51, s39, s75
	s_cselect_b32 s50, s73, s74
	s_add_i32 m0, s21, 0xc000
	s_nop 0
	global_load_lds_dwordx4 v166, s[48:49]
	s_add_i32 m0, s21, 0xe000
	s_nop 0
	global_load_lds_dwordx4 v170, s[48:49]
	s_waitcnt vmcnt(10)
	s_barrier
	s_waitcnt lgkmcnt(0)
	v_mfma_f32_16x16x32_bf16 v[126:129], v[130:133], v[146:149], v[126:129]
	ds_read_b128 v[192:195], v242
	v_mfma_f32_16x16x32_bf16 v[122:125], v[138:141], v[146:149], v[122:125]
	v_mfma_f32_16x16x32_bf16 v[118:121], v[130:133], v[154:157], v[118:121]
	v_mfma_f32_16x16x32_bf16 v[114:117], v[138:141], v[154:157], v[114:117]
	v_mfma_f32_16x16x32_bf16 v[106:109], v[130:133], v[176:179], v[106:109]
	ds_read_b128 v[196:199], v242 offset:1024
	v_mfma_f32_16x16x32_bf16 v[98:101], v[138:141], v[176:179], v[98:101]
	v_mfma_f32_16x16x32_bf16 v[90:93], v[130:133], v[184:187], v[90:93]
	v_mfma_f32_16x16x32_bf16 v[82:85], v[138:141], v[184:187], v[82:85]
	v_mfma_f32_16x16x32_bf16 v[126:129], v[134:137], v[150:153], v[126:129]
	ds_read_b128 v[200:203], v242 offset:2048
	v_mfma_f32_16x16x32_bf16 v[122:125], v[142:145], v[150:153], v[122:125]
	v_mfma_f32_16x16x32_bf16 v[118:121], v[134:137], v[158:161], v[118:121]
	v_mfma_f32_16x16x32_bf16 v[114:117], v[142:145], v[158:161], v[114:117]
	v_mfma_f32_16x16x32_bf16 v[106:109], v[134:137], v[180:183], v[106:109]
	ds_read_b128 v[204:207], v242 offset:3072
	v_mfma_f32_16x16x32_bf16 v[98:101], v[142:145], v[180:183], v[98:101]
	v_mfma_f32_16x16x32_bf16 v[90:93], v[134:137], v[188:191], v[90:93]
	v_mfma_f32_16x16x32_bf16 v[82:85], v[142:145], v[188:191], v[82:85]
	s_barrier
	s_add_i32 s81, s68, s56
	s_add_u32 s96, s50, 0x80
	s_addc_u32 s97, s51, 0
	s_mov_b32 m0, s81
	s_nop 0
	global_load_lds_dwordx4 v162, s[50:51]
	s_add_i32 m0, s81, 0x2000
	s_nop 0
	global_load_lds_dwordx4 v164, s[50:51]
	s_waitcnt vmcnt(10)
	s_barrier
	s_waitcnt lgkmcnt(0)
	v_mfma_f32_16x16x32_bf16 v[110:113], v[192:195], v[146:149], v[110:113]
	ds_read_b128 v[208:211], v241 offset:16384
	v_mfma_f32_16x16x32_bf16 v[102:105], v[200:203], v[146:149], v[102:105]
	v_mfma_f32_16x16x32_bf16 v[94:97], v[192:195], v[154:157], v[94:97]
	ds_read_b128 v[212:215], v241 offset:17408
	v_mfma_f32_16x16x32_bf16 v[86:89], v[200:203], v[154:157], v[86:89]
	v_mfma_f32_16x16x32_bf16 v[78:81], v[192:195], v[176:179], v[78:81]
	ds_read_b128 v[216:219], v241 offset:18432
	v_mfma_f32_16x16x32_bf16 v[74:77], v[200:203], v[176:179], v[74:77]
	v_mfma_f32_16x16x32_bf16 v[70:73], v[192:195], v[184:187], v[70:73]
	ds_read_b128 v[220:223], v241 offset:19456
	v_mfma_f32_16x16x32_bf16 v[66:69], v[200:203], v[184:187], v[66:69]
	v_mfma_f32_16x16x32_bf16 v[110:113], v[196:199], v[150:153], v[110:113]
	ds_read_b128 v[224:227], v241 offset:20480
	v_mfma_f32_16x16x32_bf16 v[102:105], v[204:207], v[150:153], v[102:105]
	v_mfma_f32_16x16x32_bf16 v[94:97], v[196:199], v[158:161], v[94:97]
	ds_read_b128 v[228:231], v241 offset:21504
	v_mfma_f32_16x16x32_bf16 v[86:89], v[204:207], v[158:161], v[86:89]
	v_mfma_f32_16x16x32_bf16 v[78:81], v[196:199], v[180:183], v[78:81]
	ds_read_b128 v[232:235], v241 offset:22528
	v_mfma_f32_16x16x32_bf16 v[74:77], v[204:207], v[180:183], v[74:77]
	v_mfma_f32_16x16x32_bf16 v[70:73], v[196:199], v[188:191], v[70:73]
	ds_read_b128 v[246:249], v241 offset:23552
	v_mfma_f32_16x16x32_bf16 v[66:69], v[204:207], v[188:191], v[66:69]
	s_barrier
	s_mov_b32 m0, s21
	s_add_u32 s94, s52, 0x80
	s_addc_u32 s95, s53, 0
	global_load_lds_dwordx4 v162, s[52:53]
	s_mov_b32 m0, s59
	s_nop 0
	global_load_lds_dwordx4 v164, s[52:53]
	s_waitcnt vmcnt(8)
	s_barrier
	s_waitcnt lgkmcnt(0)
	v_mfma_f32_16x16x32_bf16 v[62:65], v[130:133], v[208:211], v[62:65]
	ds_read_b128 v[146:149], v241 offset:32768
	v_mfma_f32_16x16x32_bf16 v[58:61], v[138:141], v[208:211], v[58:61]
	v_mfma_f32_16x16x32_bf16 v[54:57], v[130:133], v[216:219], v[54:57]
	ds_read_b128 v[150:153], v241 offset:33792
	v_mfma_f32_16x16x32_bf16 v[50:53], v[138:141], v[216:219], v[50:53]
	v_mfma_f32_16x16x32_bf16 v[42:45], v[130:133], v[224:227], v[42:45]
	ds_read_b128 v[154:157], v241 offset:34816
	v_mfma_f32_16x16x32_bf16 v[34:37], v[138:141], v[224:227], v[34:37]
	v_mfma_f32_16x16x32_bf16 v[26:29], v[130:133], v[232:235], v[26:29]
	ds_read_b128 v[158:161], v241 offset:35840
	v_mfma_f32_16x16x32_bf16 v[18:21], v[138:141], v[232:235], v[18:21]
	v_mfma_f32_16x16x32_bf16 v[62:65], v[134:137], v[212:215], v[62:65]
	ds_read_b128 v[176:179], v241 offset:36864
	v_mfma_f32_16x16x32_bf16 v[58:61], v[142:145], v[212:215], v[58:61]
	v_mfma_f32_16x16x32_bf16 v[54:57], v[134:137], v[220:223], v[54:57]
	ds_read_b128 v[180:183], v241 offset:37888
	v_mfma_f32_16x16x32_bf16 v[50:53], v[142:145], v[220:223], v[50:53]
	v_mfma_f32_16x16x32_bf16 v[42:45], v[134:137], v[228:231], v[42:45]
	ds_read_b128 v[184:187], v241 offset:38912
	v_mfma_f32_16x16x32_bf16 v[34:37], v[142:145], v[228:231], v[34:37]
	v_mfma_f32_16x16x32_bf16 v[26:29], v[134:137], v[246:249], v[26:29]
	ds_read_b128 v[188:191], v241 offset:39936
	v_mfma_f32_16x16x32_bf16 v[18:21], v[142:145], v[246:249], v[18:21]
	s_barrier
	s_add_u32 s82, s50, 0x80000
	s_addc_u32 s83, s51, 0
	s_add_i32 s81, s69, s56
	s_mov_b32 m0, s81
	s_nop 0
	global_load_lds_dwordx4 v162, s[82:83]
	s_add_i32 m0, s81, 0x2000
	s_nop 0
	global_load_lds_dwordx4 v164, s[82:83]
	s_waitcnt vmcnt(10)
	s_barrier
	s_waitcnt lgkmcnt(0)
	v_mfma_f32_16x16x32_bf16 v[46:49], v[192:195], v[208:211], v[46:49]
	ds_read_b128 v[130:133], v168
	v_mfma_f32_16x16x32_bf16 v[38:41], v[200:203], v[208:211], v[38:41]
	v_mfma_f32_16x16x32_bf16 v[30:33], v[192:195], v[216:219], v[30:33]
	v_mfma_f32_16x16x32_bf16 v[22:25], v[200:203], v[216:219], v[22:25]
	v_mfma_f32_16x16x32_bf16 v[14:17], v[192:195], v[224:227], v[14:17]
	ds_read_b128 v[134:137], v168 offset:1024
	v_mfma_f32_16x16x32_bf16 v[10:13], v[200:203], v[224:227], v[10:13]
	v_mfma_f32_16x16x32_bf16 v[6:9], v[192:195], v[232:235], v[6:9]
	v_mfma_f32_16x16x32_bf16 v[2:5], v[200:203], v[232:235], v[2:5]
	v_mfma_f32_16x16x32_bf16 v[46:49], v[196:199], v[212:215], v[46:49]
	ds_read_b128 v[138:141], v168 offset:2048
	v_mfma_f32_16x16x32_bf16 v[38:41], v[204:207], v[212:215], v[38:41]
	v_mfma_f32_16x16x32_bf16 v[30:33], v[196:199], v[220:223], v[30:33]
	v_mfma_f32_16x16x32_bf16 v[22:25], v[204:207], v[220:223], v[22:25]
	v_mfma_f32_16x16x32_bf16 v[14:17], v[196:199], v[228:231], v[14:17]
	ds_read_b128 v[142:145], v168 offset:3072
	v_mfma_f32_16x16x32_bf16 v[10:13], v[204:207], v[228:231], v[10:13]
	v_mfma_f32_16x16x32_bf16 v[6:9], v[196:199], v[246:249], v[6:9]
	v_mfma_f32_16x16x32_bf16 v[2:5], v[204:207], v[246:249], v[2:5]
	s_barrier
	s_add_i32 s81, 0, 0x18000
	s_add_u32 s52, s52, 0x80000
	s_addc_u32 s53, s53, 0
	s_mov_b32 m0, s60
	s_nop 0
	global_load_lds_dwordx4 v162, s[52:53]
	s_mov_b32 m0, s61
	s_nop 0
	global_load_lds_dwordx4 v164, s[52:53]
	s_waitcnt vmcnt(10)
	s_barrier
	s_waitcnt lgkmcnt(0)
	v_mfma_f32_16x16x32_bf16 v[126:129], v[130:133], v[146:149], v[126:129]
	ds_read_b128 v[192:195], v169
	v_mfma_f32_16x16x32_bf16 v[122:125], v[138:141], v[146:149], v[122:125]
	v_mfma_f32_16x16x32_bf16 v[118:121], v[130:133], v[154:157], v[118:121]
	v_mfma_f32_16x16x32_bf16 v[114:117], v[138:141], v[154:157], v[114:117]
	v_mfma_f32_16x16x32_bf16 v[106:109], v[130:133], v[176:179], v[106:109]
	ds_read_b128 v[196:199], v169 offset:1024
	v_mfma_f32_16x16x32_bf16 v[98:101], v[138:141], v[176:179], v[98:101]
	v_mfma_f32_16x16x32_bf16 v[90:93], v[130:133], v[184:187], v[90:93]
	v_mfma_f32_16x16x32_bf16 v[82:85], v[138:141], v[184:187], v[82:85]
	v_mfma_f32_16x16x32_bf16 v[126:129], v[134:137], v[150:153], v[126:129]
	ds_read_b128 v[200:203], v169 offset:2048
	v_mfma_f32_16x16x32_bf16 v[122:125], v[142:145], v[150:153], v[122:125]
	v_mfma_f32_16x16x32_bf16 v[118:121], v[134:137], v[158:161], v[118:121]
	v_mfma_f32_16x16x32_bf16 v[114:117], v[142:145], v[158:161], v[114:117]
	v_mfma_f32_16x16x32_bf16 v[106:109], v[134:137], v[180:183], v[106:109]
	ds_read_b128 v[204:207], v169 offset:3072
	v_mfma_f32_16x16x32_bf16 v[98:101], v[142:145], v[180:183], v[98:101]
	v_mfma_f32_16x16x32_bf16 v[90:93], v[134:137], v[188:191], v[90:93]
	v_mfma_f32_16x16x32_bf16 v[82:85], v[142:145], v[188:191], v[82:85]
	s_barrier
	s_add_i32 s52, 0, 0x1c000
	s_add_i32 s53, s81, s56
	s_mov_b32 m0, s53
	s_nop 0
	global_load_lds_dwordx4 v162, s[96:97]
	s_add_i32 m0, s53, 0x2000
	s_nop 0
	global_load_lds_dwordx4 v164, s[96:97]
	s_waitcnt vmcnt(10)
	s_barrier
	s_waitcnt lgkmcnt(0)
	v_mfma_f32_16x16x32_bf16 v[110:113], v[192:195], v[146:149], v[110:113]
	ds_read_b128 v[208:211], v241 offset:49152
	v_mfma_f32_16x16x32_bf16 v[102:105], v[200:203], v[146:149], v[102:105]
	v_mfma_f32_16x16x32_bf16 v[94:97], v[192:195], v[154:157], v[94:97]
	ds_read_b128 v[212:215], v241 offset:50176
	v_mfma_f32_16x16x32_bf16 v[86:89], v[200:203], v[154:157], v[86:89]
	v_mfma_f32_16x16x32_bf16 v[78:81], v[192:195], v[176:179], v[78:81]
	ds_read_b128 v[216:219], v241 offset:51200
	v_mfma_f32_16x16x32_bf16 v[74:77], v[200:203], v[176:179], v[74:77]
	v_mfma_f32_16x16x32_bf16 v[70:73], v[192:195], v[184:187], v[70:73]
	ds_read_b128 v[220:223], v241 offset:52224
	v_mfma_f32_16x16x32_bf16 v[66:69], v[200:203], v[184:187], v[66:69]
	v_mfma_f32_16x16x32_bf16 v[110:113], v[196:199], v[150:153], v[110:113]
	ds_read_b128 v[224:227], v241 offset:53248
	v_mfma_f32_16x16x32_bf16 v[102:105], v[204:207], v[150:153], v[102:105]
	v_mfma_f32_16x16x32_bf16 v[94:97], v[196:199], v[158:161], v[94:97]
	ds_read_b128 v[228:231], v241 offset:54272
	v_mfma_f32_16x16x32_bf16 v[86:89], v[204:207], v[158:161], v[86:89]
	v_mfma_f32_16x16x32_bf16 v[78:81], v[196:199], v[180:183], v[78:81]
	ds_read_b128 v[232:235], v241 offset:55296
	v_mfma_f32_16x16x32_bf16 v[74:77], v[204:207], v[180:183], v[74:77]
	v_mfma_f32_16x16x32_bf16 v[70:73], v[196:199], v[188:191], v[70:73]
	ds_read_b128 v[246:249], v241 offset:56320
	v_mfma_f32_16x16x32_bf16 v[66:69], v[204:207], v[188:191], v[66:69]
	s_barrier
	s_mov_b32 m0, s64
	s_nop 0
	global_load_lds_dwordx4 v162, s[94:95]
	s_mov_b32 m0, s65
	s_nop 0
	global_load_lds_dwordx4 v164, s[94:95]
	s_waitcnt vmcnt(8)
	s_barrier
	s_waitcnt lgkmcnt(0)
	v_mfma_f32_16x16x32_bf16 v[62:65], v[130:133], v[208:211], v[62:65]
	ds_read_b128 v[146:149], v241
	v_mfma_f32_16x16x32_bf16 v[58:61], v[138:141], v[208:211], v[58:61]
	v_mfma_f32_16x16x32_bf16 v[54:57], v[130:133], v[216:219], v[54:57]
	ds_read_b128 v[150:153], v241 offset:1024
	v_mfma_f32_16x16x32_bf16 v[50:53], v[138:141], v[216:219], v[50:53]
	v_mfma_f32_16x16x32_bf16 v[42:45], v[130:133], v[224:227], v[42:45]
	ds_read_b128 v[154:157], v241 offset:2048
	v_mfma_f32_16x16x32_bf16 v[34:37], v[138:141], v[224:227], v[34:37]
	v_mfma_f32_16x16x32_bf16 v[26:29], v[130:133], v[232:235], v[26:29]
	ds_read_b128 v[158:161], v241 offset:3072
	v_mfma_f32_16x16x32_bf16 v[18:21], v[138:141], v[232:235], v[18:21]
	v_mfma_f32_16x16x32_bf16 v[62:65], v[134:137], v[212:215], v[62:65]
	ds_read_b128 v[176:179], v241 offset:4096
	v_mfma_f32_16x16x32_bf16 v[58:61], v[142:145], v[212:215], v[58:61]
	v_mfma_f32_16x16x32_bf16 v[54:57], v[134:137], v[220:223], v[54:57]
	ds_read_b128 v[180:183], v241 offset:5120
	v_mfma_f32_16x16x32_bf16 v[50:53], v[142:145], v[220:223], v[50:53]
	v_mfma_f32_16x16x32_bf16 v[42:45], v[134:137], v[228:231], v[42:45]
	ds_read_b128 v[184:187], v241 offset:6144
	v_mfma_f32_16x16x32_bf16 v[34:37], v[142:145], v[228:231], v[34:37]
	v_mfma_f32_16x16x32_bf16 v[26:29], v[134:137], v[246:249], v[26:29]
	ds_read_b128 v[188:191], v241 offset:7168
	v_mfma_f32_16x16x32_bf16 v[18:21], v[142:145], v[246:249], v[18:21]
	s_barrier
	s_add_u32 s50, s50, 0x80080
	s_addc_u32 s51, s51, 0
	s_add_i32 s52, s52, s56
	s_mov_b32 m0, s52
	s_nop 0
	global_load_lds_dwordx4 v162, s[50:51]
	s_add_i32 m0, s52, 0x2000
	s_nop 0
	global_load_lds_dwordx4 v164, s[50:51]
	s_waitcnt vmcnt(10)
	s_barrier
	s_waitcnt lgkmcnt(0)
	v_mfma_f32_16x16x32_bf16 v[46:49], v[192:195], v[208:211], v[46:49]
	ds_read_b128 v[130:133], v240
	v_mfma_f32_16x16x32_bf16 v[38:41], v[200:203], v[208:211], v[38:41]
	v_mfma_f32_16x16x32_bf16 v[30:33], v[192:195], v[216:219], v[30:33]
	v_mfma_f32_16x16x32_bf16 v[22:25], v[200:203], v[216:219], v[22:25]
	v_mfma_f32_16x16x32_bf16 v[14:17], v[192:195], v[224:227], v[14:17]
	ds_read_b128 v[134:137], v240 offset:1024
	v_mfma_f32_16x16x32_bf16 v[10:13], v[200:203], v[224:227], v[10:13]
	v_mfma_f32_16x16x32_bf16 v[6:9], v[192:195], v[232:235], v[6:9]
	v_mfma_f32_16x16x32_bf16 v[2:5], v[200:203], v[232:235], v[2:5]
	v_mfma_f32_16x16x32_bf16 v[46:49], v[196:199], v[212:215], v[46:49]
	ds_read_b128 v[138:141], v240 offset:2048
	v_mfma_f32_16x16x32_bf16 v[38:41], v[204:207], v[212:215], v[38:41]
	v_mfma_f32_16x16x32_bf16 v[30:33], v[196:199], v[220:223], v[30:33]
	v_mfma_f32_16x16x32_bf16 v[22:25], v[204:207], v[220:223], v[22:25]
	v_mfma_f32_16x16x32_bf16 v[14:17], v[196:199], v[228:231], v[14:17]
	ds_read_b128 v[142:145], v240 offset:3072
	v_mfma_f32_16x16x32_bf16 v[10:13], v[204:207], v[228:231], v[10:13]
	v_mfma_f32_16x16x32_bf16 v[6:9], v[196:199], v[246:249], v[6:9]
	v_mfma_f32_16x16x32_bf16 v[2:5], v[204:207], v[246:249], v[2:5]
	s_add_i32 s80, s80, 2
	s_add_u32 s48, s48, 0x100
	s_addc_u32 s49, s49, 0
	s_add_u32 s74, s74, 0x100
	s_addc_u32 s75, s75, 0
	s_cmp_gt_u32 s80, s87
	s_barrier
	s_cbranch_scc0 .LBB0_1098

.LBB0_1143:
	s_setprio 0
	s_waitcnt vmcnt(0)
	s_cmpk_gt_u32 s54, 0xff
	s_cbranch_scc1 .LBB0_1145
	s_barrier
